# in-proj and residual K-loops peeled like FFN-in; MIX2 attention: static s_setprio 1 for the second token-half waves
# speedup vs baseline: 1.0115x; 1.0025x over previous
.LBB0_305:
	v_lshl_add_u64 v[4:5], s[6:7], 0, v[178:179]
	v_mov_b64_e32 v[6:7], s[82:83]
	v_mad_u64_u32 v[8:9], s[8:9], v4, s85, v[6:7]
	v_mov_b32_e32 v4, v9
	s_lshl_b32 s11, s11, 6
	v_mad_u64_u32 v[4:5], s[8:9], v5, s85, v[4:5]
	v_mov_b32_e32 v9, v4
	s_lshl_b32 s80, s11, 1
	v_lshl_add_u64 v[4:5], v[8:9], 0, s[80:81]
	v_lshl_add_u64 v[4:5], v[4:5], 0, v[0:1]
	global_load_dwordx4 v[162:165], v[4:5], off offset:1024
	global_load_dwordx4 v[166:169], v[4:5], off offset:1280
	v_lshl_add_u64 v[4:5], s[6:7], 0, v[180:181]
	v_mad_u64_u32 v[6:7], s[6:7], v4, s85, v[6:7]
	v_mov_b32_e32 v4, v7
	v_mad_u64_u32 v[4:5], s[6:7], v5, s85, v[4:5]
	v_mov_b32_e32 v7, v4
	v_lshl_add_u64 v[4:5], v[6:7], 0, s[80:81]
	v_lshl_add_u64 v[4:5], v[4:5], 0, v[0:1]
	global_load_dwordx4 v[170:173], v[4:5], off offset:1024
	global_load_dwordx4 v[174:177], v[4:5], off offset:1280
	s_lshl_b32 s20, s10, 6
	s_add_i32 s24, s22, 0xffffff80
	s_add_i32 s25, s22, 0xbf
	s_add_i32 s26, s22, 0xffffffbf
	s_add_i32 s27, s22, 0x41
	v_lshlrev_b32_e32 v200, 3, v3
	v_mul_f32_e32 v186, 0x3fb8aa3b, v2
	v_lshlrev_b32_e32 v2, 2, v3
	v_lshrrev_b32_e32 v3, 2, v187
	s_add_u32 s6, s82, s80
	v_and_b32_e32 v183, 63, v187
	v_and_or_b32 v202, v3, 3, v2
	v_lshlrev_b32_e32 v3, 2, v187
	v_sub_u32_e32 v2, v2, v189
	s_addc_u32 s7, s83, 0
	v_mov_b32_e32 v14, v1
	v_mov_b32_e32 v15, v1
	v_cmp_gt_u32_e32 vcc, 32, v183
	v_and_b32_e32 v16, 16, v187
	v_and_b32_e32 v17, 12, v3
	v_add_u32_e32 v203, 0x80, v2
	v_lshl_add_u64 v[184:185], s[6:7], 0, v[0:1]
	v_mov_b32_e32 v0, v1
	v_mov_b32_e32 v2, v1
	v_mov_b32_e32 v3, v1
	v_mov_b32_e32 v4, v1
	v_mov_b32_e32 v5, v1
	v_mov_b32_e32 v6, v1
	v_mov_b32_e32 v7, v1
	v_mov_b32_e32 v8, v1
	v_mov_b32_e32 v9, v1
	v_mov_b32_e32 v10, v1
	v_mov_b32_e32 v11, v1
	v_mov_b32_e32 v12, v1
	v_mov_b32_e32 v13, v1
	v_mov_b64_e32 v[64:65], v[14:15]
	v_mov_b64_e32 v[32:33], v[14:15]
	v_mov_b64_e32 v[48:49], v[14:15]
	v_cndmask_b32_e64 v201, 0, 1.0, vcc
	v_lshlrev_b32_e32 v204, 1, v16
	v_lshlrev_b32_e32 v205, 1, v17
	v_mov_b64_e32 v[62:63], v[12:13]
	v_mov_b64_e32 v[60:61], v[10:11]
	v_mov_b64_e32 v[58:59], v[8:9]
	v_mov_b64_e32 v[56:57], v[6:7]
	v_mov_b64_e32 v[54:55], v[4:5]
	v_mov_b64_e32 v[52:53], v[2:3]
	v_mov_b64_e32 v[50:51], v[0:1]
	v_mov_b64_e32 v[30:31], v[12:13]
	v_mov_b64_e32 v[28:29], v[10:11]
	v_mov_b64_e32 v[26:27], v[8:9]
	v_mov_b64_e32 v[24:25], v[6:7]
	v_mov_b64_e32 v[22:23], v[4:5]
	v_mov_b64_e32 v[20:21], v[2:3]
	v_mov_b64_e32 v[18:19], v[0:1]
	v_mov_b64_e32 v[46:47], v[12:13]
	v_mov_b64_e32 v[44:45], v[10:11]
	v_mov_b64_e32 v[42:43], v[8:9]
	v_mov_b64_e32 v[40:41], v[6:7]
	v_mov_b64_e32 v[38:39], v[4:5]
	v_mov_b64_e32 v[36:37], v[2:3]
	v_mov_b64_e32 v[34:35], v[0:1]
	v_mov_b64_e32 v[16:17], v[14:15]
	s_mov_b32 s28, 0
	v_mov_b32_e32 v199, v201
	v_mov_b32_e32 v188, v186
	v_mov_b64_e32 v[14:15], v[12:13]
	v_mov_b64_e32 v[12:13], v[10:11]
	v_mov_b64_e32 v[10:11], v[8:9]
	v_mov_b64_e32 v[8:9], v[6:7]
	v_mov_b64_e32 v[6:7], v[4:5]
	v_mov_b64_e32 v[4:5], v[2:3]
	v_mov_b64_e32 v[2:3], v[0:1]
	s_waitcnt lgkmcnt(0)
	s_barrier
	v_readfirstlane_b32 s99, v244
	s_lshr_b32 s99, s99, 8
	s_cmp_eq_u32 s99, 1
	s_cbranch_scc0 .Lap_skip
	s_setprio 1
.Lap_skip:
.LBB0_306:
	s_cmp_lt_i32 s21, 5
	s_cselect_b64 s[6:7], -1, 0
	s_cmp_gt_i32 s21, 4
	s_cselect_b64 s[8:9], -1, 0
	s_mov_b32 s29, 5
	s_and_b64 vcc, exec, s[8:9]
	s_mov_b32 s12, s21
	s_cbranch_vccz .LBB0_308
	s_branch .LBB0_310

.LBB0_347:
	s_setprio 0
	v_mov_b32_e32 v0, v201
	s_nop 1
	v_permlane32_swap_b32_e32 v201, v0
	v_add_f32_e32 v0, v201, v0
	v_div_scale_f32 v66, s[4:5], v0, v0, 1.0
	v_rcp_f32_e32 v67, v66
	s_mulk_i32 s18, 0x2400
	s_add_i32 s6, s18, 0
	s_mov_b64 s[28:29], s[42:43]
	v_fma_f32 v68, -v66, v67, 1.0
	v_fmac_f32_e32 v67, v68, v67
	v_div_scale_f32 v68, vcc, 1.0, v0, 1.0
	v_mul_f32_e32 v69, v68, v67
	v_fma_f32 v70, -v66, v69, v68
	v_fmac_f32_e32 v69, v70, v67
	v_fma_f32 v66, -v66, v69, v68
	v_div_fmas_f32 v66, v66, v67, v69
	v_div_fixup_f32 v0, v66, v0, 1.0
	v_mul_f32_e32 v50, v50, v0
	v_mul_f32_e32 v51, v51, v0
	v_mul_u32_u24_e32 v66, 0x90, v189
	v_cvt_pk_bf16_f32 v50, v50, v51
	v_mul_f32_e32 v51, v52, v0
	v_add3_u32 v66, s6, v200, v66
	v_mul_f32_e32 v52, v53, v0
	v_cvt_pk_bf16_f32 v51, v51, v52
	ds_write_b64 v66, v[50:51]
	v_mul_f32_e32 v50, v54, v0
	v_mul_f32_e32 v51, v55, v0
	v_cvt_pk_bf16_f32 v50, v50, v51
	v_mul_f32_e32 v51, v56, v0
	v_mul_f32_e32 v52, v57, v0
	v_cvt_pk_bf16_f32 v51, v51, v52
	ds_write_b64 v66, v[50:51] offset:16
	v_mul_f32_e32 v50, v58, v0
	v_mul_f32_e32 v51, v59, v0
	v_cvt_pk_bf16_f32 v50, v50, v51
	v_mul_f32_e32 v51, v60, v0
	v_mul_f32_e32 v52, v61, v0
	v_cvt_pk_bf16_f32 v51, v51, v52
	ds_write_b64 v66, v[50:51] offset:32
	v_mul_f32_e32 v50, v62, v0
	v_mul_f32_e32 v51, v63, v0
	v_cvt_pk_bf16_f32 v50, v50, v51
	v_mul_f32_e32 v51, v64, v0
	v_mul_f32_e32 v34, v34, v0
	v_mul_f32_e32 v35, v35, v0
	v_mul_f32_e32 v52, v65, v0
	v_cvt_pk_bf16_f32 v51, v51, v52
	ds_write_b64 v66, v[50:51] offset:48
	v_cvt_pk_bf16_f32 v34, v34, v35
	v_mul_f32_e32 v35, v36, v0
	v_mul_f32_e32 v36, v37, v0
	v_cvt_pk_bf16_f32 v35, v35, v36
	ds_write_b64 v66, v[34:35] offset:64
	v_mul_f32_e32 v34, v38, v0
	v_mul_f32_e32 v35, v39, v0
	v_cvt_pk_bf16_f32 v34, v34, v35
	v_mul_f32_e32 v35, v40, v0
	v_mul_f32_e32 v36, v41, v0
	v_cvt_pk_bf16_f32 v35, v35, v36
	ds_write_b64 v66, v[34:35] offset:80
	v_mul_f32_e32 v34, v42, v0
	v_mul_f32_e32 v35, v43, v0
	v_cvt_pk_bf16_f32 v34, v34, v35
	v_mul_f32_e32 v35, v44, v0
	v_mul_f32_e32 v36, v45, v0
	v_cvt_pk_bf16_f32 v35, v35, v36
	v_mov_b32_e32 v36, v199
	s_nop 1
	v_permlane32_swap_b32_e32 v199, v36
	v_add_f32_e32 v36, v199, v36
	v_div_scale_f32 v37, s[4:5], v36, v36, 1.0
	v_rcp_f32_e32 v38, v37
	ds_write_b64 v66, v[34:35] offset:96
	v_mul_f32_e32 v34, v46, v0
	v_mul_f32_e32 v35, v47, v0
	v_cvt_pk_bf16_f32 v34, v34, v35
	v_mul_f32_e32 v35, v48, v0
	v_mul_f32_e32 v0, v49, v0
	v_cvt_pk_bf16_f32 v35, v35, v0
	v_fma_f32 v0, -v37, v38, 1.0
	v_fmac_f32_e32 v38, v0, v38
	v_div_scale_f32 v0, vcc, 1.0, v36, 1.0
	ds_write_b64 v66, v[34:35] offset:112
	v_mul_f32_e32 v34, v0, v38
	v_fma_f32 v35, -v37, v34, v0
	v_fmac_f32_e32 v34, v35, v38
	v_fma_f32 v0, -v37, v34, v0
	v_div_fmas_f32 v0, v0, v38, v34
	v_div_fixup_f32 v0, v0, v36, 1.0
	v_mul_f32_e32 v18, v18, v0
	v_mul_f32_e32 v19, v19, v0
	v_cvt_pk_bf16_f32 v18, v18, v19
	v_mul_f32_e32 v19, v20, v0
	v_mul_f32_e32 v20, v21, v0
	v_cvt_pk_bf16_f32 v19, v19, v20
	ds_write_b64 v66, v[18:19] offset:4608
	v_mul_f32_e32 v18, v22, v0
	v_mul_f32_e32 v19, v23, v0
	v_cvt_pk_bf16_f32 v18, v18, v19
	v_mul_f32_e32 v19, v24, v0
	v_mul_f32_e32 v20, v25, v0
	v_cvt_pk_bf16_f32 v19, v19, v20
	ds_write_b64 v66, v[18:19] offset:4624
	v_mul_f32_e32 v18, v26, v0
	v_mul_f32_e32 v19, v27, v0
	v_cvt_pk_bf16_f32 v18, v18, v19
	v_mul_f32_e32 v19, v28, v0
	v_mul_f32_e32 v20, v29, v0
	v_cvt_pk_bf16_f32 v19, v19, v20
	ds_write_b64 v66, v[18:19] offset:4640
	v_mul_f32_e32 v18, v30, v0
	v_mul_f32_e32 v19, v31, v0
	v_cvt_pk_bf16_f32 v18, v18, v19
	v_mul_f32_e32 v19, v32, v0
	v_mul_f32_e32 v2, v2, v0
	v_mul_f32_e32 v3, v3, v0
	v_mul_f32_e32 v20, v33, v0
	v_cvt_pk_bf16_f32 v19, v19, v20
	ds_write_b64 v66, v[18:19] offset:4656
	v_cvt_pk_bf16_f32 v2, v2, v3
	v_mul_f32_e32 v3, v4, v0
	v_mul_f32_e32 v4, v5, v0
	v_cvt_pk_bf16_f32 v3, v3, v4
	ds_write_b64 v66, v[2:3] offset:4672
	v_mul_f32_e32 v2, v6, v0
	v_mul_f32_e32 v3, v7, v0
	v_cvt_pk_bf16_f32 v2, v2, v3
	v_mul_f32_e32 v3, v8, v0
	v_mul_f32_e32 v4, v9, v0
	v_cvt_pk_bf16_f32 v3, v3, v4
	ds_write_b64 v66, v[2:3] offset:4688
	v_mul_f32_e32 v2, v10, v0
	v_mul_f32_e32 v3, v11, v0
	v_cvt_pk_bf16_f32 v2, v2, v3
	v_mul_f32_e32 v3, v12, v0
	v_mul_f32_e32 v4, v13, v0
	v_cvt_pk_bf16_f32 v3, v3, v4
	ds_write_b64 v66, v[2:3] offset:4704
	v_mul_f32_e32 v2, v14, v0
	v_mul_f32_e32 v3, v15, v0
	v_cvt_pk_bf16_f32 v2, v2, v3
	v_mul_f32_e32 v3, v16, v0
	v_mul_f32_e32 v0, v17, v0
	s_lshl_b32 s4, s20, 1
	v_cvt_pk_bf16_f32 v3, v3, v0
	v_lshrrev_b32_e32 v6, 3, v183
	v_lshlrev_b32_e32 v0, 4, v187
	s_add_u32 s4, s92, s4
	ds_write_b64 v66, v[2:3] offset:4720
	v_and_b32_e32 v0, 0x70, v0
	s_addc_u32 s5, s93, 0
	v_mul_u32_u24_e32 v2, 0x90, v6
	s_waitcnt lgkmcnt(0)
	v_lshl_add_u64 v[10:11], s[4:5], 0, v[0:1]
	v_add3_u32 v0, s6, v0, v2
	ds_read_b128 v[2:5], v0
	v_or_b32_e32 v12, s3, v6
	v_mov_b32_e32 v13, s16
	v_lshlrev_b64 v[6:7], 11, v[12:13]
	v_lshl_add_u64 v[14:15], v[10:11], 0, v[6:7]
	ds_read_b128 v[6:9], v0 offset:1152
	s_waitcnt lgkmcnt(1)
	global_store_dwordx4 v[14:15], v[2:5], off
	s_mov_b64 s[4:5], -1
	v_writelane_b32 v254, s4, 37
	v_or_b32_e32 v2, 8, v12
	v_mov_b32_e32 v3, s16
	v_lshlrev_b64 v[2:3], 11, v[2:3]
	v_lshl_add_u64 v[2:3], v[10:11], 0, v[2:3]
	s_waitcnt lgkmcnt(0)
	global_store_dwordx4 v[2:3], v[6:9], off
	ds_read_b128 v[2:5], v0 offset:2304
	v_writelane_b32 v254, s5, 38
	v_or_b32_e32 v6, 16, v12
	v_mov_b32_e32 v7, s16
	v_lshlrev_b64 v[6:7], 11, v[6:7]
	v_lshl_add_u64 v[14:15], v[10:11], 0, v[6:7]
	ds_read_b128 v[6:9], v0 offset:3456
	s_waitcnt lgkmcnt(1)
	global_store_dwordx4 v[14:15], v[2:5], off
	v_readlane_b32 s26, v254, 15
	v_readlane_b32 s12, v254, 56
	v_or_b32_e32 v2, 24, v12
	v_mov_b32_e32 v3, s16
	v_lshlrev_b64 v[2:3], 11, v[2:3]
	v_lshl_add_u64 v[2:3], v[10:11], 0, v[2:3]
	s_waitcnt lgkmcnt(0)
	global_store_dwordx4 v[2:3], v[6:9], off
	ds_read_b128 v[2:5], v0 offset:4608
	v_readlane_b32 s27, v254, 16
	v_or_b32_e32 v6, 32, v12
	v_mov_b32_e32 v7, s16
	v_lshlrev_b64 v[6:7], 11, v[6:7]
	v_lshl_add_u64 v[14:15], v[10:11], 0, v[6:7]
	ds_read_b128 v[6:9], v0 offset:5760
	s_waitcnt lgkmcnt(1)
	global_store_dwordx4 v[14:15], v[2:5], off
	v_readlane_b32 s13, v254, 57
	s_mov_b64 s[6:7], 0
	v_or_b32_e32 v2, 40, v12
	v_mov_b32_e32 v3, s16
	v_lshlrev_b64 v[2:3], 11, v[2:3]
	v_lshl_add_u64 v[2:3], v[10:11], 0, v[2:3]
	s_waitcnt lgkmcnt(0)
	global_store_dwordx4 v[2:3], v[6:9], off
	ds_read_b128 v[2:5], v0 offset:6912
	s_nop 0
	v_or_b32_e32 v6, 48, v12
	v_mov_b32_e32 v7, s16
	v_lshlrev_b64 v[6:7], 11, v[6:7]
	v_lshl_add_u64 v[14:15], v[10:11], 0, v[6:7]
	ds_read_b128 v[6:9], v0 offset:8064
	v_or_b32_e32 v12, 56, v12
	s_waitcnt lgkmcnt(1)
	global_store_dwordx4 v[14:15], v[2:5], off
	s_nop 1
	v_lshlrev_b64 v[2:3], 11, v[12:13]
	v_lshl_add_u64 v[2:3], v[10:11], 0, v[2:3]
	s_waitcnt lgkmcnt(0)
	global_store_dwordx4 v[2:3], v[6:9], off
	s_barrier
	s_branch .LBB0_335

.LBB0_475:
	s_ashr_i32 s29, s28, 31
	s_lshl_b64 s[16:17], s[28:29], 19
	s_add_u32 s30, s92, s16
	s_addc_u32 s31, s93, s17
	s_and_b64 s[16:17], s[8:9], exec
	s_cselect_b32 s5, s31, s15
	s_cselect_b32 s13, s30, s14
	s_ashr_i32 s25, s24, 31
	s_lshl_b64 s[16:17], s[24:25], 19
	v_readlane_b32 s34, v254, 43
	v_readlane_b32 s35, v254, 44
	s_add_u32 s36, s34, s16
	s_addc_u32 s37, s35, s17
	s_and_b64 s[16:17], s[8:9], exec
	s_cselect_b32 s25, s37, s11
	s_cselect_b32 s29, s36, s10
	s_add_u32 s34, s10, 0x100
	s_addc_u32 s35, s11, 0
	s_add_u32 s10, s14, 0x40080
	s_addc_u32 s11, s15, 0
	s_mov_b32 s38, -2
	s_waitcnt vmcnt(0)
	s_add_u32 s14, s10, 0xfffc0080
	s_addc_u32 s15, s11, -1
	s_add_i32 s39, 0, 0x10000
	s_cmp_eq_u32 s38, 12
	s_cselect_b32 s17, s5, s15
	s_cselect_b32 s16, s13, s14
	v_add_u32_e32 v0, s39, v251
	s_cselect_b32 s15, s25, s35
	s_cselect_b32 s14, s29, s34
	s_add_i32 s42, 0, 0x14000
	ds_read_b128 v[2:5], v0
	ds_read_b128 v[6:9], v0 offset:1024
	ds_read_b128 v[34:37], v0 offset:2048
	ds_read_b128 v[38:41], v0 offset:3072
	v_add_u32_e32 v0, s42, v251
	ds_read_b128 v[50:53], v0
	ds_read_b128 v[54:57], v0 offset:1024
	ds_read_b128 v[66:69], v0 offset:2048
	ds_read_b128 v[70:73], v0 offset:3072
	v_lshl_add_u64 v[138:139], s[10:11], 0, v[228:229]
	s_add_i32 m0, s47, 0xc000
	ds_read_b128 v[82:85], v241
	ds_read_b128 v[86:89], v241 offset:1024
	ds_read_b128 v[98:101], v241 offset:2048
	ds_read_b128 v[102:105], v241 offset:3072
	ds_read_b128 v[114:117], v241 offset:4096
	ds_read_b128 v[118:121], v241 offset:5120
	ds_read_b128 v[122:125], v241 offset:6144
	ds_read_b128 v[126:129], v241 offset:7168
	global_load_lds_dwordx4 v[138:139], off
	v_lshl_add_u64 v[138:139], s[10:11], 0, v[226:227]
	s_add_i32 m0, s47, 0xe000
	s_nop 0
	global_load_lds_dwordx4 v[138:139], off
	s_waitcnt vmcnt(8)
	s_waitcnt lgkmcnt(0)
	s_barrier
	s_setprio 1
	s_waitcnt lgkmcnt(0)
	v_mfma_f32_16x16x32_bf16 v[190:193], v[2:5], v[114:117], 0
	v_mfma_f32_16x16x32_bf16 v[186:189], v[34:37], v[114:117], 0
	v_mfma_f32_16x16x32_bf16 v[182:185], v[2:5], v[122:125], 0
	v_mfma_f32_16x16x32_bf16 v[178:181], v[34:37], v[122:125], 0
	v_mfma_f32_16x16x32_bf16 v[138:141], v[2:5], v[82:85], 0
	v_mfma_f32_16x16x32_bf16 v[142:145], v[34:37], v[82:85], 0
	v_mfma_f32_16x16x32_bf16 v[162:165], v[2:5], v[98:101], 0
	v_mfma_f32_16x16x32_bf16 v[166:169], v[34:37], v[98:101], 0
	v_mfma_f32_16x16x32_bf16 v[190:193], v[6:9], v[118:121], v[190:193]
	v_mfma_f32_16x16x32_bf16 v[186:189], v[38:41], v[118:121], v[186:189]
	v_mfma_f32_16x16x32_bf16 v[182:185], v[6:9], v[126:129], v[182:185]
	v_mfma_f32_16x16x32_bf16 v[178:181], v[38:41], v[126:129], v[178:181]
	v_mfma_f32_16x16x32_bf16 v[138:141], v[6:9], v[86:89], v[138:141]
	v_mfma_f32_16x16x32_bf16 v[142:145], v[38:41], v[86:89], v[142:145]
	v_mfma_f32_16x16x32_bf16 v[162:165], v[6:9], v[102:105], v[162:165]
	v_mfma_f32_16x16x32_bf16 v[166:169], v[38:41], v[102:105], v[166:169]
	s_setprio 0
	s_setprio 1
	v_mfma_f32_16x16x32_bf16 v[110:113], v[50:53], v[82:85], 0
	v_mfma_f32_16x16x32_bf16 v[82:85], v[66:69], v[82:85], 0
	v_mfma_f32_16x16x32_bf16 v[90:93], v[66:69], v[98:101], 0
	v_mfma_f32_16x16x32_bf16 v[78:81], v[50:53], v[114:117], 0
	v_mfma_f32_16x16x32_bf16 v[74:77], v[66:69], v[114:117], 0
	v_mfma_f32_16x16x32_bf16 v[62:65], v[50:53], v[122:125], 0
	v_mfma_f32_16x16x32_bf16 v[58:61], v[66:69], v[122:125], 0
	v_mfma_f32_16x16x32_bf16 v[110:113], v[54:57], v[86:89], v[110:113]
	v_mfma_f32_16x16x32_bf16 v[82:85], v[70:73], v[86:89], v[82:85]
	v_mfma_f32_16x16x32_bf16 v[86:89], v[50:53], v[98:101], 0
	v_mfma_f32_16x16x32_bf16 v[90:93], v[70:73], v[102:105], v[90:93]
	v_mfma_f32_16x16x32_bf16 v[78:81], v[54:57], v[118:121], v[78:81]
	v_mfma_f32_16x16x32_bf16 v[74:77], v[70:73], v[118:121], v[74:77]
	v_mfma_f32_16x16x32_bf16 v[62:65], v[54:57], v[126:129], v[62:65]
	v_mfma_f32_16x16x32_bf16 v[58:61], v[70:73], v[126:129], v[58:61]
	v_mfma_f32_16x16x32_bf16 v[86:89], v[54:57], v[102:105], v[86:89]
	s_setprio 0
	s_barrier
	s_add_i32 s39, s39, s46
	v_lshl_add_u64 v[230:231], s[14:15], 0, v[212:213]
	s_mov_b32 m0, s39
	ds_read_b128 v[94:97], v241 offset:16384
	ds_read_b128 v[98:101], v241 offset:17408
	ds_read_b128 v[102:105], v241 offset:18432
	ds_read_b128 v[106:109], v241 offset:19456
	ds_read_b128 v[114:117], v241 offset:20480
	ds_read_b128 v[118:121], v241 offset:21504
	ds_read_b128 v[122:125], v241 offset:22528
	ds_read_b128 v[126:129], v241 offset:23552
	global_load_lds_dwordx4 v[230:231], off
	s_add_i32 m0, s39, 0x2000
	s_add_u32 s40, s14, 0x40000
	v_lshl_add_u64 v[232:233], s[14:15], 0, v[216:217]
	s_addc_u32 s41, s15, 0
	s_add_i32 s39, s42, s46
	global_load_lds_dwordx4 v[232:233], off
	v_lshl_add_u64 v[194:195], s[40:41], 0, v[212:213]
	s_mov_b32 m0, s39
	v_lshl_add_u64 v[234:235], s[16:17], 0, v[210:211]
	global_load_lds_dwordx4 v[194:195], off
	v_lshl_add_u64 v[194:195], s[40:41], 0, v[216:217]
	s_add_i32 m0, s39, 0x2000
	v_lshl_add_u64 v[236:237], s[16:17], 0, v[214:215]
	global_load_lds_dwordx4 v[194:195], off
	s_mov_b32 m0, s47
	s_nop 0
	global_load_lds_dwordx4 v[234:235], off
	s_mov_b32 m0, s48
	s_nop 0
	global_load_lds_dwordx4 v[236:237], off
	s_waitcnt vmcnt(8)
	s_waitcnt lgkmcnt(0)
	s_barrier
	s_setprio 1
	s_waitcnt lgkmcnt(0)
	v_mfma_f32_16x16x32_bf16 v[174:177], v[2:5], v[94:97], 0
	v_mfma_f32_16x16x32_bf16 v[170:173], v[34:37], v[94:97], 0
	v_mfma_f32_16x16x32_bf16 v[158:161], v[2:5], v[102:105], 0
	v_mfma_f32_16x16x32_bf16 v[154:157], v[34:37], v[102:105], 0
	v_mfma_f32_16x16x32_bf16 v[150:153], v[2:5], v[114:117], 0
	v_mfma_f32_16x16x32_bf16 v[146:149], v[34:37], v[114:117], 0
	v_mfma_f32_16x16x32_bf16 v[2:5], v[2:5], v[122:125], 0
	v_mfma_f32_16x16x32_bf16 v[174:177], v[6:9], v[98:101], v[174:177]
	v_mfma_f32_16x16x32_bf16 v[170:173], v[38:41], v[98:101], v[170:173]
	v_mfma_f32_16x16x32_bf16 v[158:161], v[6:9], v[106:109], v[158:161]
	v_mfma_f32_16x16x32_bf16 v[154:157], v[38:41], v[106:109], v[154:157]
	v_mfma_f32_16x16x32_bf16 v[150:153], v[6:9], v[118:121], v[150:153]
	v_mfma_f32_16x16x32_bf16 v[146:149], v[38:41], v[118:121], v[146:149]
	v_mfma_f32_16x16x32_bf16 v[2:5], v[6:9], v[126:129], v[2:5]
	v_mfma_f32_16x16x32_bf16 v[6:9], v[34:37], v[122:125], 0
	v_mfma_f32_16x16x32_bf16 v[6:9], v[38:41], v[126:129], v[6:9]
	s_setprio 0
	s_setprio 1
	v_mfma_f32_16x16x32_bf16 v[30:33], v[50:53], v[102:105], 0
	v_mfma_f32_16x16x32_bf16 v[26:29], v[66:69], v[102:105], 0
	v_mfma_f32_16x16x32_bf16 v[22:25], v[50:53], v[114:117], 0
	v_mfma_f32_16x16x32_bf16 v[18:21], v[66:69], v[114:117], 0
	v_mfma_f32_16x16x32_bf16 v[14:17], v[50:53], v[122:125], 0
	v_mfma_f32_16x16x32_bf16 v[10:13], v[66:69], v[122:125], 0
	v_mfma_f32_16x16x32_bf16 v[34:37], v[50:53], v[94:97], 0
	v_mfma_f32_16x16x32_bf16 v[38:41], v[66:69], v[94:97], 0
	v_mfma_f32_16x16x32_bf16 v[30:33], v[54:57], v[106:109], v[30:33]
	v_mfma_f32_16x16x32_bf16 v[26:29], v[70:73], v[106:109], v[26:29]
	v_mfma_f32_16x16x32_bf16 v[22:25], v[54:57], v[118:121], v[22:25]
	v_mfma_f32_16x16x32_bf16 v[18:21], v[70:73], v[118:121], v[18:21]
	v_mfma_f32_16x16x32_bf16 v[14:17], v[54:57], v[126:129], v[14:17]
	v_mfma_f32_16x16x32_bf16 v[10:13], v[70:73], v[126:129], v[10:13]
	v_mfma_f32_16x16x32_bf16 v[34:37], v[54:57], v[98:101], v[34:37]
	v_mfma_f32_16x16x32_bf16 v[38:41], v[70:73], v[98:101], v[38:41]
	s_setprio 0
	s_barrier
	s_add_i32 s39, 0, 0x18000
	v_add_u32_e32 v0, s39, v251
	s_add_i32 s40, 0, 0x1c000
	ds_read_b128 v[42:45], v0
	ds_read_b128 v[46:49], v0 offset:1024
	ds_read_b128 v[50:53], v0 offset:2048
	ds_read_b128 v[54:57], v0 offset:3072
	v_add_u32_e32 v0, s40, v251
	ds_read_b128 v[66:69], v0
	ds_read_b128 v[70:73], v0 offset:1024
	ds_read_b128 v[98:101], v0 offset:2048
	ds_read_b128 v[102:105], v0 offset:3072
	s_add_u32 s16, s16, 0x40000
	s_addc_u32 s17, s17, 0
	s_mov_b32 m0, s49
	v_lshl_add_u64 v[194:195], s[16:17], 0, v[210:211]
	ds_read_b128 v[94:97], v241 offset:32768
	ds_read_b128 v[106:109], v241 offset:33792
	ds_read_b128 v[114:117], v241 offset:34816
	ds_read_b128 v[118:121], v241 offset:35840
	ds_read_b128 v[122:125], v241 offset:36864
	ds_read_b128 v[126:129], v241 offset:37888
	ds_read_b128 v[130:133], v241 offset:38912
	ds_read_b128 v[134:137], v241 offset:39936
	global_load_lds_dwordx4 v[194:195], off
	v_lshl_add_u64 v[194:195], s[16:17], 0, v[214:215]
	s_mov_b32 m0, s61
	s_nop 0
	global_load_lds_dwordx4 v[194:195], off
	s_waitcnt vmcnt(8)
	s_waitcnt lgkmcnt(0)
	s_barrier
	s_setprio 1
	s_waitcnt lgkmcnt(0)
	v_mfma_f32_16x16x32_bf16 v[138:141], v[42:45], v[94:97], v[138:141]
	v_mfma_f32_16x16x32_bf16 v[206:209], v[46:49], v[106:109], v[138:141]
	v_mfma_f32_16x16x32_bf16 v[138:141], v[50:53], v[94:97], v[142:145]
	v_mfma_f32_16x16x32_bf16 v[202:205], v[54:57], v[106:109], v[138:141]
	v_mfma_f32_16x16x32_bf16 v[138:141], v[42:45], v[114:117], v[162:165]
	v_mfma_f32_16x16x32_bf16 v[198:201], v[46:49], v[118:121], v[138:141]
	v_mfma_f32_16x16x32_bf16 v[138:141], v[50:53], v[114:117], v[166:169]
	v_mfma_f32_16x16x32_bf16 v[194:197], v[54:57], v[118:121], v[138:141]
	v_mfma_f32_16x16x32_bf16 v[138:141], v[42:45], v[122:125], v[190:193]
	v_mfma_f32_16x16x32_bf16 v[190:193], v[46:49], v[126:129], v[138:141]
	v_mfma_f32_16x16x32_bf16 v[138:141], v[50:53], v[122:125], v[186:189]
	v_mfma_f32_16x16x32_bf16 v[186:189], v[54:57], v[126:129], v[138:141]
	v_mfma_f32_16x16x32_bf16 v[138:141], v[42:45], v[130:133], v[182:185]
	v_mfma_f32_16x16x32_bf16 v[182:185], v[46:49], v[134:137], v[138:141]
	v_mfma_f32_16x16x32_bf16 v[138:141], v[50:53], v[130:133], v[178:181]
	v_mfma_f32_16x16x32_bf16 v[178:181], v[54:57], v[134:137], v[138:141]
	s_setprio 0
	s_setprio 1
	v_mfma_f32_16x16x32_bf16 v[110:113], v[66:69], v[94:97], v[110:113]
	v_mfma_f32_16x16x32_bf16 v[82:85], v[98:101], v[94:97], v[82:85]
	v_mfma_f32_16x16x32_bf16 v[110:113], v[70:73], v[106:109], v[110:113]
	v_mfma_f32_16x16x32_bf16 v[106:109], v[102:105], v[106:109], v[82:85]
	v_mfma_f32_16x16x32_bf16 v[82:85], v[66:69], v[114:117], v[86:89]
	v_mfma_f32_16x16x32_bf16 v[94:97], v[70:73], v[118:121], v[82:85]
	v_mfma_f32_16x16x32_bf16 v[82:85], v[98:101], v[114:117], v[90:93]
	v_mfma_f32_16x16x32_bf16 v[78:81], v[66:69], v[122:125], v[78:81]
	v_mfma_f32_16x16x32_bf16 v[74:77], v[98:101], v[122:125], v[74:77]
	v_mfma_f32_16x16x32_bf16 v[62:65], v[66:69], v[130:133], v[62:65]
	v_mfma_f32_16x16x32_bf16 v[58:61], v[98:101], v[130:133], v[58:61]
	v_mfma_f32_16x16x32_bf16 v[90:93], v[102:105], v[118:121], v[82:85]
	v_mfma_f32_16x16x32_bf16 v[78:81], v[70:73], v[126:129], v[78:81]
	v_mfma_f32_16x16x32_bf16 v[74:77], v[102:105], v[126:129], v[74:77]
	v_mfma_f32_16x16x32_bf16 v[62:65], v[70:73], v[134:137], v[62:65]
	v_mfma_f32_16x16x32_bf16 v[58:61], v[102:105], v[134:137], v[58:61]
	s_setprio 0
	s_barrier
	s_add_i32 s16, s39, s46
	v_lshl_add_u64 v[130:131], v[230:231], 0, s[76:77]
	s_mov_b32 m0, s16
	ds_read_b128 v[82:85], v241 offset:49152
	ds_read_b128 v[86:89], v241 offset:50176
	ds_read_b128 v[114:117], v241 offset:51200
	ds_read_b128 v[118:121], v241 offset:52224
	ds_read_b128 v[122:125], v241 offset:53248
	ds_read_b128 v[126:129], v241 offset:54272
	ds_read_b128 v[138:141], v241 offset:55296
	ds_read_b128 v[142:145], v241 offset:56320
	global_load_lds_dwordx4 v[130:131], off
	s_add_i32 m0, s16, 0x2000
	s_add_u32 s14, s14, 0x40080
	v_lshl_add_u64 v[130:131], v[232:233], 0, s[76:77]
	s_addc_u32 s15, s15, 0
	s_add_i32 s16, s40, s46
	global_load_lds_dwordx4 v[130:131], off
	v_lshl_add_u64 v[130:131], s[14:15], 0, v[212:213]
	s_mov_b32 m0, s16
	s_nop 0
	global_load_lds_dwordx4 v[130:131], off
	v_lshl_add_u64 v[130:131], s[14:15], 0, v[216:217]
	s_add_i32 m0, s16, 0x2000
	s_nop 0
	global_load_lds_dwordx4 v[130:131], off
	v_lshl_add_u64 v[130:131], v[234:235], 0, s[76:77]
	s_mov_b32 m0, s63
	s_nop 0
	global_load_lds_dwordx4 v[130:131], off
	v_lshl_add_u64 v[130:131], v[236:237], 0, s[76:77]
	s_mov_b32 m0, s70
	s_nop 0
	global_load_lds_dwordx4 v[130:131], off
	s_waitcnt vmcnt(8)
	s_waitcnt lgkmcnt(0)
	s_barrier
	s_setprio 1
	s_waitcnt lgkmcnt(0)
	v_mfma_f32_16x16x32_bf16 v[130:133], v[42:45], v[82:85], v[174:177]
	v_mfma_f32_16x16x32_bf16 v[174:177], v[46:49], v[86:89], v[130:133]
	v_mfma_f32_16x16x32_bf16 v[130:133], v[50:53], v[82:85], v[170:173]
	v_mfma_f32_16x16x32_bf16 v[170:173], v[54:57], v[86:89], v[130:133]
	v_mfma_f32_16x16x32_bf16 v[130:133], v[42:45], v[114:117], v[158:161]
	v_mfma_f32_16x16x32_bf16 v[158:161], v[46:49], v[118:121], v[130:133]
	v_mfma_f32_16x16x32_bf16 v[130:133], v[50:53], v[114:117], v[154:157]
	v_mfma_f32_16x16x32_bf16 v[154:157], v[54:57], v[118:121], v[130:133]
	v_mfma_f32_16x16x32_bf16 v[130:133], v[42:45], v[122:125], v[150:153]
	v_mfma_f32_16x16x32_bf16 v[2:5], v[42:45], v[138:141], v[2:5]
	v_mfma_f32_16x16x32_bf16 v[150:153], v[46:49], v[126:129], v[130:133]
	v_mfma_f32_16x16x32_bf16 v[130:133], v[50:53], v[122:125], v[146:149]
	v_mfma_f32_16x16x32_bf16 v[134:137], v[46:49], v[142:145], v[2:5]
	v_mfma_f32_16x16x32_bf16 v[2:5], v[50:53], v[138:141], v[6:9]
	v_mfma_f32_16x16x32_bf16 v[146:149], v[54:57], v[126:129], v[130:133]
	v_mfma_f32_16x16x32_bf16 v[130:133], v[54:57], v[142:145], v[2:5]
	s_setprio 0
	s_setprio 1
	v_mfma_f32_16x16x32_bf16 v[2:5], v[66:69], v[82:85], v[34:37]
	v_mfma_f32_16x16x32_bf16 v[46:49], v[70:73], v[86:89], v[2:5]
	v_mfma_f32_16x16x32_bf16 v[2:5], v[98:101], v[82:85], v[38:41]
	v_mfma_f32_16x16x32_bf16 v[42:45], v[102:105], v[86:89], v[2:5]
	v_mfma_f32_16x16x32_bf16 v[2:5], v[66:69], v[114:117], v[30:33]
	v_mfma_f32_16x16x32_bf16 v[30:33], v[70:73], v[118:121], v[2:5]
	v_mfma_f32_16x16x32_bf16 v[2:5], v[98:101], v[114:117], v[26:29]
	v_mfma_f32_16x16x32_bf16 v[26:29], v[102:105], v[118:121], v[2:5]
	v_mfma_f32_16x16x32_bf16 v[2:5], v[66:69], v[122:125], v[22:25]
	v_mfma_f32_16x16x32_bf16 v[22:25], v[70:73], v[126:129], v[2:5]
	v_mfma_f32_16x16x32_bf16 v[2:5], v[98:101], v[122:125], v[18:21]
	v_mfma_f32_16x16x32_bf16 v[18:21], v[102:105], v[126:129], v[2:5]
	v_mfma_f32_16x16x32_bf16 v[2:5], v[66:69], v[138:141], v[14:17]
	v_mfma_f32_16x16x32_bf16 v[14:17], v[70:73], v[142:145], v[2:5]
	v_mfma_f32_16x16x32_bf16 v[2:5], v[98:101], v[138:141], v[10:13]
	v_mfma_f32_16x16x32_bf16 v[10:13], v[102:105], v[142:145], v[2:5]
	s_setprio 0
	s_barrier
	s_add_i32 s38, s38, 2
	s_add_u32 s34, s34, 0x100
	s_addc_u32 s35, s35, 0
	s_add_u32 s10, s10, 0x100
	s_addc_u32 s11, s11, 0
	s_cmp_gt_u32 s38, 13

.LBB0_748:
	v_lshl_add_u64 v[8:9], s[4:5], 0, v[0:1]
	v_mov_b32_e32 v135, v1
	v_lshl_add_u64 v[10:11], s[4:5], 0, v[134:135]
	v_mov_b32_e32 v131, v1
	s_add_i32 m0, s91, 0x18000
	v_lshl_add_u64 v[8:9], v[8:9], 0, s[76:77]
	v_lshl_add_u64 v[16:17], s[18:19], 0, v[130:131]
	v_mov_b32_e32 v133, v1
	s_waitcnt vmcnt(2)
	s_barrier
	global_load_lds_dwordx4 v[8:9], off
	v_lshl_add_u64 v[8:9], v[10:11], 0, s[76:77]
	s_add_i32 m0, s91, 0x1a000
	s_add_i32 s35, s91, 0x8000
	v_lshl_add_u64 v[18:19], s[18:19], 0, v[132:133]
	global_load_lds_dwordx4 v[8:9], off
	v_lshl_add_u64 v[8:9], v[16:17], 0, s[76:77]
	s_mov_b32 m0, s35
	s_add_i32 s48, s91, 0xa000
	v_lshl_add_u64 v[12:13], s[10:11], 0, v[0:1]
	global_load_lds_dwordx4 v[8:9], off
	v_lshl_add_u64 v[8:9], v[18:19], 0, s[76:77]
	s_mov_b32 m0, s48
	v_lshl_add_u64 v[14:15], s[10:11], 0, v[134:135]
	global_load_lds_dwordx4 v[8:9], off
	s_add_i32 m0, s91, 0x1c000
	v_lshl_add_u64 v[8:9], v[12:13], 0, s[76:77]
	global_load_lds_dwordx4 v[8:9], off
	v_lshl_add_u64 v[8:9], v[14:15], 0, s[76:77]
	s_add_i32 m0, s91, 0x1e000
	s_xor_b64 s[38:39], s[8:9], -1
	global_load_lds_dwordx4 v[8:9], off
	s_lshr_b32 s8, s12, 3
	v_and_b32_e32 v164, 15, v163
	v_and_b32_e32 v20, 48, v163
	v_lshlrev_b32_e32 v21, 2, v163
	s_sext_i32_i8 s28, s8
	s_and_b32 s45, s29, 3
	s_lshl_b32 s8, s44, 13
	v_lshl_or_b32 v20, v164, 6, v20
	v_and_b32_e32 v21, 32, v21
	s_lshr_b32 s51, s7, 6
	s_lshl_b32 s80, s44, 6
	v_bitop3_b32 v22, v20, s8, v21 bitop3:0xde
	s_lshl_b32 s8, s45, 12
	s_add_i32 s34, s51, -2
	v_bitop3_b32 v144, v20, s8, v21 bitop3:0xde
	s_add_u32 s8, s87, 0x80
	v_add_u32_e32 v2, v4, v2
	s_waitcnt vmcnt(6)
	s_addc_u32 s9, 0, 0
	v_add_u32_e32 v5, v7, v5
	v_add_lshl_u32 v2, v2, v3, 1
	v_mov_b32_e32 v3, v1
	v_add_lshl_u32 v6, v5, v6, 1
	v_mov_b32_e32 v7, v1
	v_lshl_add_u64 v[138:139], s[8:9], 0, v[2:3]
	v_or_b32_e32 v162, s80, v164
	v_lshl_add_u64 v[136:137], s[8:9], 0, v[6:7]
	s_mov_b32 s49, 0
	v_add_u32_e32 v145, 0, v22
	s_barrier
	s_branch .LBB0_750

.LBB0_760:
	s_mov_b32 s42, 0
	s_mov_b64 s[40:41], 0x100
	v_mov_b64_e32 v[140:141], v[138:139]
	v_mov_b64_e32 v[142:143], v[136:137]
	s_add_i32 vcc_lo, s42, 2
	s_add_u32 s62, s18, s40
	s_addc_u32 s43, s19, s41
	s_add_u32 vcc_hi, s4, s40
	s_addc_u32 s63, s5, s41
	s_add_i32 s95, 0, 0x10000
	s_cmp_eq_u32 s34, s42
	s_cselect_b32 s43, s13, s43
	s_cselect_b32 s42, s12, s62
	v_add_u32_e32 v160, s95, v144
	s_cselect_b32 s63, s37, s63
	s_cselect_b32 s62, s36, vcc_hi
	s_add_i32 vcc_hi, 0, 0x14000
	ds_read_b128 v[148:151], v160
	ds_read_b128 v[152:155], v160 offset:1024
	ds_read_b128 v[156:159], v160 offset:2048
	ds_read_b128 v[166:169], v160 offset:3072
	v_add_u32_e32 v160, vcc_hi, v144
	ds_read_b128 v[170:173], v160
	ds_read_b128 v[174:177], v160 offset:1024
	ds_read_b128 v[178:181], v160 offset:2048
	ds_read_b128 v[182:185], v160 offset:3072
	v_lshl_add_u64 v[160:161], s[18:19], 0, v[140:141]
	s_add_i32 m0, s91, 0xc000
	ds_read_b128 v[186:189], v145
	ds_read_b128 v[190:193], v145 offset:1024
	ds_read_b128 v[194:197], v145 offset:2048
	ds_read_b128 v[198:201], v145 offset:3072
	ds_read_b128 v[202:205], v145 offset:4096
	ds_read_b128 v[206:209], v145 offset:5120
	ds_read_b128 v[210:213], v145 offset:6144
	ds_read_b128 v[214:217], v145 offset:7168
	global_load_lds_dwordx4 v[160:161], off
	v_lshl_add_u64 v[160:161], s[18:19], 0, v[142:143]
	s_add_i32 m0, s91, 0xe000
	s_nop 0
	global_load_lds_dwordx4 v[160:161], off
	s_waitcnt vmcnt(8)
	s_waitcnt lgkmcnt(0)
	s_barrier
	s_setprio 1
	s_waitcnt lgkmcnt(0)
	v_mfma_f32_16x16x32_bf16 v[126:129], v[148:151], v[186:189], 0
	v_mfma_f32_16x16x32_bf16 v[122:125], v[156:159], v[186:189], 0
	v_mfma_f32_16x16x32_bf16 v[118:121], v[148:151], v[194:197], 0
	v_mfma_f32_16x16x32_bf16 v[114:117], v[156:159], v[194:197], 0
	v_mfma_f32_16x16x32_bf16 v[110:113], v[148:151], v[202:205], 0
	v_mfma_f32_16x16x32_bf16 v[106:109], v[156:159], v[202:205], 0
	v_mfma_f32_16x16x32_bf16 v[102:105], v[148:151], v[210:213], 0
	v_mfma_f32_16x16x32_bf16 v[98:101], v[156:159], v[210:213], 0
	v_mfma_f32_16x16x32_bf16 v[126:129], v[152:155], v[190:193], v[126:129]
	v_mfma_f32_16x16x32_bf16 v[122:125], v[166:169], v[190:193], v[122:125]
	v_mfma_f32_16x16x32_bf16 v[118:121], v[152:155], v[198:201], v[118:121]
	v_mfma_f32_16x16x32_bf16 v[114:117], v[166:169], v[198:201], v[114:117]
	v_mfma_f32_16x16x32_bf16 v[110:113], v[152:155], v[206:209], v[110:113]
	v_mfma_f32_16x16x32_bf16 v[106:109], v[166:169], v[206:209], v[106:109]
	v_mfma_f32_16x16x32_bf16 v[102:105], v[152:155], v[214:217], v[102:105]
	v_mfma_f32_16x16x32_bf16 v[98:101], v[166:169], v[214:217], v[98:101]
	s_setprio 0
	s_setprio 1
	v_mfma_f32_16x16x32_bf16 v[66:69], v[170:173], v[186:189], 0
	v_mfma_f32_16x16x32_bf16 v[58:61], v[178:181], v[186:189], 0
	v_mfma_f32_16x16x32_bf16 v[54:57], v[170:173], v[194:197], 0
	v_mfma_f32_16x16x32_bf16 v[50:53], v[178:181], v[194:197], 0
	v_mfma_f32_16x16x32_bf16 v[46:49], v[170:173], v[202:205], 0
	v_mfma_f32_16x16x32_bf16 v[42:45], v[178:181], v[202:205], 0
	v_mfma_f32_16x16x32_bf16 v[38:41], v[170:173], v[210:213], 0
	v_mfma_f32_16x16x32_bf16 v[34:37], v[178:181], v[210:213], 0
	v_mfma_f32_16x16x32_bf16 v[66:69], v[174:177], v[190:193], v[66:69]
	v_mfma_f32_16x16x32_bf16 v[58:61], v[182:185], v[190:193], v[58:61]
	v_mfma_f32_16x16x32_bf16 v[54:57], v[174:177], v[198:201], v[54:57]
	v_mfma_f32_16x16x32_bf16 v[50:53], v[182:185], v[198:201], v[50:53]
	v_mfma_f32_16x16x32_bf16 v[46:49], v[174:177], v[206:209], v[46:49]
	v_mfma_f32_16x16x32_bf16 v[42:45], v[182:185], v[206:209], v[42:45]
	v_mfma_f32_16x16x32_bf16 v[38:41], v[174:177], v[214:217], v[38:41]
	v_mfma_f32_16x16x32_bf16 v[34:37], v[182:185], v[214:217], v[34:37]
	s_setprio 0
	s_barrier
	s_add_i32 s95, s95, s86
	v_lshl_add_u64 v[160:161], s[62:63], 0, v[0:1]
	s_mov_b32 m0, s95
	ds_read_b128 v[186:189], v145 offset:16384
	ds_read_b128 v[190:193], v145 offset:17408
	ds_read_b128 v[194:197], v145 offset:18432
	ds_read_b128 v[198:201], v145 offset:19456
	ds_read_b128 v[202:205], v145 offset:20480
	ds_read_b128 v[206:209], v145 offset:21504
	ds_read_b128 v[210:213], v145 offset:22528
	ds_read_b128 v[214:217], v145 offset:23552
	global_load_lds_dwordx4 v[160:161], off
	s_add_i32 m0, s95, 0x2000
	v_lshl_add_u64 v[222:223], s[62:63], 0, v[134:135]
	s_add_u32 s62, s62, s87
	s_addc_u32 s63, s63, 0
	s_add_i32 s95, vcc_hi, s86
	global_load_lds_dwordx4 v[222:223], off
	v_lshl_add_u64 v[224:225], s[62:63], 0, v[0:1]
	s_mov_b32 m0, s95
	v_lshl_add_u64 v[226:227], s[62:63], 0, v[134:135]
	global_load_lds_dwordx4 v[224:225], off
	s_add_i32 m0, s95, 0x2000
	v_lshl_add_u64 v[228:229], s[42:43], 0, v[130:131]
	global_load_lds_dwordx4 v[226:227], off
	s_mov_b32 m0, s91
	v_lshl_add_u64 v[230:231], s[42:43], 0, v[132:133]
	global_load_lds_dwordx4 v[228:229], off
	s_mov_b32 m0, s52
	s_nop 0
	global_load_lds_dwordx4 v[230:231], off
	s_waitcnt vmcnt(8)
	s_waitcnt lgkmcnt(0)
	s_barrier
	s_setprio 1
	s_waitcnt lgkmcnt(0)
	v_mfma_f32_16x16x32_bf16 v[94:97], v[148:151], v[186:189], 0
	v_mfma_f32_16x16x32_bf16 v[90:93], v[156:159], v[186:189], 0
	v_mfma_f32_16x16x32_bf16 v[86:89], v[148:151], v[194:197], 0
	v_mfma_f32_16x16x32_bf16 v[82:85], v[156:159], v[194:197], 0
	v_mfma_f32_16x16x32_bf16 v[78:81], v[148:151], v[202:205], 0
	v_mfma_f32_16x16x32_bf16 v[74:77], v[156:159], v[202:205], 0
	v_mfma_f32_16x16x32_bf16 v[70:73], v[148:151], v[210:213], 0
	v_mfma_f32_16x16x32_bf16 v[62:65], v[156:159], v[210:213], 0
	v_mfma_f32_16x16x32_bf16 v[94:97], v[152:155], v[190:193], v[94:97]
	v_mfma_f32_16x16x32_bf16 v[90:93], v[166:169], v[190:193], v[90:93]
	v_mfma_f32_16x16x32_bf16 v[86:89], v[152:155], v[198:201], v[86:89]
	v_mfma_f32_16x16x32_bf16 v[82:85], v[166:169], v[198:201], v[82:85]
	v_mfma_f32_16x16x32_bf16 v[78:81], v[152:155], v[206:209], v[78:81]
	v_mfma_f32_16x16x32_bf16 v[74:77], v[166:169], v[206:209], v[74:77]
	v_mfma_f32_16x16x32_bf16 v[70:73], v[152:155], v[214:217], v[70:73]
	v_mfma_f32_16x16x32_bf16 v[62:65], v[166:169], v[214:217], v[62:65]
	s_setprio 0
	s_setprio 1
	v_mfma_f32_16x16x32_bf16 v[30:33], v[170:173], v[186:189], 0
	v_mfma_f32_16x16x32_bf16 v[26:29], v[178:181], v[186:189], 0
	v_mfma_f32_16x16x32_bf16 v[22:25], v[170:173], v[194:197], 0
	v_mfma_f32_16x16x32_bf16 v[18:21], v[178:181], v[194:197], 0
	v_mfma_f32_16x16x32_bf16 v[14:17], v[170:173], v[202:205], 0
	v_mfma_f32_16x16x32_bf16 v[10:13], v[178:181], v[202:205], 0
	v_mfma_f32_16x16x32_bf16 v[6:9], v[170:173], v[210:213], 0
	v_mfma_f32_16x16x32_bf16 v[2:5], v[178:181], v[210:213], 0
	v_mfma_f32_16x16x32_bf16 v[30:33], v[174:177], v[190:193], v[30:33]
	v_mfma_f32_16x16x32_bf16 v[26:29], v[182:185], v[190:193], v[26:29]
	v_mfma_f32_16x16x32_bf16 v[22:25], v[174:177], v[198:201], v[22:25]
	v_mfma_f32_16x16x32_bf16 v[18:21], v[182:185], v[198:201], v[18:21]
	v_mfma_f32_16x16x32_bf16 v[14:17], v[174:177], v[206:209], v[14:17]
	v_mfma_f32_16x16x32_bf16 v[10:13], v[182:185], v[206:209], v[10:13]
	v_mfma_f32_16x16x32_bf16 v[6:9], v[174:177], v[214:217], v[6:9]
	v_mfma_f32_16x16x32_bf16 v[2:5], v[182:185], v[214:217], v[2:5]
	s_setprio 0
	s_barrier
	s_add_i32 s62, 0, 0x18000
	v_add_u32_e32 v165, s62, v144
	s_add_i32 s63, 0, 0x1c000
	ds_read_b128 v[148:151], v165
	ds_read_b128 v[152:155], v165 offset:1024
	ds_read_b128 v[156:159], v165 offset:2048
	ds_read_b128 v[166:169], v165 offset:3072
	v_add_u32_e32 v165, s63, v144
	ds_read_b128 v[170:173], v165
	ds_read_b128 v[174:177], v165 offset:1024
	ds_read_b128 v[178:181], v165 offset:2048
	ds_read_b128 v[182:185], v165 offset:3072
	s_add_u32 s42, s42, s87
	s_addc_u32 s43, s43, 0
	s_mov_b32 m0, s53
	v_lshl_add_u64 v[232:233], s[42:43], 0, v[130:131]
	ds_read_b128 v[186:189], v145 offset:32768
	ds_read_b128 v[190:193], v145 offset:33792
	ds_read_b128 v[194:197], v145 offset:34816
	ds_read_b128 v[198:201], v145 offset:35840
	ds_read_b128 v[202:205], v145 offset:36864
	ds_read_b128 v[206:209], v145 offset:37888
	ds_read_b128 v[210:213], v145 offset:38912
	ds_read_b128 v[214:217], v145 offset:39936
	global_load_lds_dwordx4 v[232:233], off
	v_lshl_add_u64 v[232:233], s[42:43], 0, v[132:133]
	s_mov_b32 m0, s50
	s_nop 0
	global_load_lds_dwordx4 v[232:233], off
	s_waitcnt vmcnt(8)
	s_waitcnt lgkmcnt(0)
	s_barrier
	s_setprio 1
	s_waitcnt lgkmcnt(0)
	v_mfma_f32_16x16x32_bf16 v[126:129], v[148:151], v[186:189], v[126:129]
	v_mfma_f32_16x16x32_bf16 v[122:125], v[156:159], v[186:189], v[122:125]
	v_mfma_f32_16x16x32_bf16 v[118:121], v[148:151], v[194:197], v[118:121]
	v_mfma_f32_16x16x32_bf16 v[114:117], v[156:159], v[194:197], v[114:117]
	v_mfma_f32_16x16x32_bf16 v[110:113], v[148:151], v[202:205], v[110:113]
	v_mfma_f32_16x16x32_bf16 v[106:109], v[156:159], v[202:205], v[106:109]
	v_mfma_f32_16x16x32_bf16 v[102:105], v[148:151], v[210:213], v[102:105]
	v_mfma_f32_16x16x32_bf16 v[98:101], v[156:159], v[210:213], v[98:101]
	v_mfma_f32_16x16x32_bf16 v[126:129], v[152:155], v[190:193], v[126:129]
	v_mfma_f32_16x16x32_bf16 v[122:125], v[166:169], v[190:193], v[122:125]
	v_mfma_f32_16x16x32_bf16 v[118:121], v[152:155], v[198:201], v[118:121]
	v_mfma_f32_16x16x32_bf16 v[114:117], v[166:169], v[198:201], v[114:117]
	v_mfma_f32_16x16x32_bf16 v[110:113], v[152:155], v[206:209], v[110:113]
	v_mfma_f32_16x16x32_bf16 v[106:109], v[166:169], v[206:209], v[106:109]
	v_mfma_f32_16x16x32_bf16 v[102:105], v[152:155], v[214:217], v[102:105]
	v_mfma_f32_16x16x32_bf16 v[98:101], v[166:169], v[214:217], v[98:101]
	s_setprio 0
	s_setprio 1
	v_mfma_f32_16x16x32_bf16 v[66:69], v[170:173], v[186:189], v[66:69]
	v_mfma_f32_16x16x32_bf16 v[58:61], v[178:181], v[186:189], v[58:61]
	v_mfma_f32_16x16x32_bf16 v[54:57], v[170:173], v[194:197], v[54:57]
	v_mfma_f32_16x16x32_bf16 v[50:53], v[178:181], v[194:197], v[50:53]
	v_mfma_f32_16x16x32_bf16 v[46:49], v[170:173], v[202:205], v[46:49]
	v_mfma_f32_16x16x32_bf16 v[42:45], v[178:181], v[202:205], v[42:45]
	v_mfma_f32_16x16x32_bf16 v[38:41], v[170:173], v[210:213], v[38:41]
	v_mfma_f32_16x16x32_bf16 v[34:37], v[178:181], v[210:213], v[34:37]
	v_mfma_f32_16x16x32_bf16 v[66:69], v[174:177], v[190:193], v[66:69]
	v_mfma_f32_16x16x32_bf16 v[58:61], v[182:185], v[190:193], v[58:61]
	v_mfma_f32_16x16x32_bf16 v[54:57], v[174:177], v[198:201], v[54:57]
	v_mfma_f32_16x16x32_bf16 v[50:53], v[182:185], v[198:201], v[50:53]
	v_mfma_f32_16x16x32_bf16 v[46:49], v[174:177], v[206:209], v[46:49]
	v_mfma_f32_16x16x32_bf16 v[42:45], v[182:185], v[206:209], v[42:45]
	v_mfma_f32_16x16x32_bf16 v[38:41], v[174:177], v[214:217], v[38:41]
	v_mfma_f32_16x16x32_bf16 v[34:37], v[182:185], v[214:217], v[34:37]
	s_setprio 0
	s_barrier
	s_add_i32 s42, s62, s86
	v_lshl_add_u64 v[160:161], v[160:161], 0, s[76:77]
	s_mov_b32 m0, s42
	ds_read_b128 v[186:189], v145 offset:49152
	ds_read_b128 v[190:193], v145 offset:50176
	ds_read_b128 v[194:197], v145 offset:51200
	ds_read_b128 v[198:201], v145 offset:52224
	ds_read_b128 v[202:205], v145 offset:53248
	ds_read_b128 v[206:209], v145 offset:54272
	ds_read_b128 v[210:213], v145 offset:55296
	ds_read_b128 v[214:217], v145 offset:56320
	global_load_lds_dwordx4 v[160:161], off
	v_lshl_add_u64 v[160:161], v[222:223], 0, s[76:77]
	s_add_i32 m0, s42, 0x2000
	s_add_i32 s42, s63, s86
	global_load_lds_dwordx4 v[160:161], off
	v_lshl_add_u64 v[160:161], v[224:225], 0, s[76:77]
	s_mov_b32 m0, s42
	s_nop 0
	global_load_lds_dwordx4 v[160:161], off
	v_lshl_add_u64 v[160:161], v[226:227], 0, s[76:77]
	s_add_i32 m0, s42, 0x2000
	s_nop 0
	global_load_lds_dwordx4 v[160:161], off
	v_lshl_add_u64 v[160:161], v[228:229], 0, s[76:77]
	s_mov_b32 m0, s35
	s_nop 0
	global_load_lds_dwordx4 v[160:161], off
	v_lshl_add_u64 v[160:161], v[230:231], 0, s[76:77]
	s_mov_b32 m0, s48
	s_nop 0
	global_load_lds_dwordx4 v[160:161], off
	s_waitcnt vmcnt(8)
	s_waitcnt lgkmcnt(0)
	s_barrier
	s_setprio 1
	s_waitcnt lgkmcnt(0)
	v_mfma_f32_16x16x32_bf16 v[94:97], v[148:151], v[186:189], v[94:97]
	v_mfma_f32_16x16x32_bf16 v[90:93], v[156:159], v[186:189], v[90:93]
	v_mfma_f32_16x16x32_bf16 v[86:89], v[148:151], v[194:197], v[86:89]
	v_mfma_f32_16x16x32_bf16 v[82:85], v[156:159], v[194:197], v[82:85]
	v_mfma_f32_16x16x32_bf16 v[78:81], v[148:151], v[202:205], v[78:81]
	v_mfma_f32_16x16x32_bf16 v[74:77], v[156:159], v[202:205], v[74:77]
	v_mfma_f32_16x16x32_bf16 v[70:73], v[148:151], v[210:213], v[70:73]
	v_mfma_f32_16x16x32_bf16 v[62:65], v[156:159], v[210:213], v[62:65]
	v_mfma_f32_16x16x32_bf16 v[94:97], v[152:155], v[190:193], v[94:97]
	v_mfma_f32_16x16x32_bf16 v[90:93], v[166:169], v[190:193], v[90:93]
	v_mfma_f32_16x16x32_bf16 v[86:89], v[152:155], v[198:201], v[86:89]
	v_mfma_f32_16x16x32_bf16 v[82:85], v[166:169], v[198:201], v[82:85]
	v_mfma_f32_16x16x32_bf16 v[78:81], v[152:155], v[206:209], v[78:81]
	v_mfma_f32_16x16x32_bf16 v[74:77], v[166:169], v[206:209], v[74:77]
	v_mfma_f32_16x16x32_bf16 v[70:73], v[152:155], v[214:217], v[70:73]
	v_mfma_f32_16x16x32_bf16 v[62:65], v[166:169], v[214:217], v[62:65]
	s_setprio 0
	s_setprio 1
	v_mfma_f32_16x16x32_bf16 v[30:33], v[170:173], v[186:189], v[30:33]
	v_mfma_f32_16x16x32_bf16 v[26:29], v[178:181], v[186:189], v[26:29]
	v_mfma_f32_16x16x32_bf16 v[22:25], v[170:173], v[194:197], v[22:25]
	v_mfma_f32_16x16x32_bf16 v[18:21], v[178:181], v[194:197], v[18:21]
	v_mfma_f32_16x16x32_bf16 v[14:17], v[170:173], v[202:205], v[14:17]
	v_mfma_f32_16x16x32_bf16 v[10:13], v[178:181], v[202:205], v[10:13]
	v_mfma_f32_16x16x32_bf16 v[6:9], v[170:173], v[210:213], v[6:9]
	v_mfma_f32_16x16x32_bf16 v[2:5], v[178:181], v[210:213], v[2:5]
	v_mfma_f32_16x16x32_bf16 v[30:33], v[174:177], v[190:193], v[30:33]
	v_mfma_f32_16x16x32_bf16 v[26:29], v[182:185], v[190:193], v[26:29]
	v_mfma_f32_16x16x32_bf16 v[22:25], v[174:177], v[198:201], v[22:25]
	v_mfma_f32_16x16x32_bf16 v[18:21], v[182:185], v[198:201], v[18:21]
	v_mfma_f32_16x16x32_bf16 v[14:17], v[174:177], v[206:209], v[14:17]
	v_mfma_f32_16x16x32_bf16 v[10:13], v[182:185], v[206:209], v[10:13]
	v_mfma_f32_16x16x32_bf16 v[6:9], v[174:177], v[214:217], v[6:9]
	v_mfma_f32_16x16x32_bf16 v[2:5], v[182:185], v[214:217], v[2:5]
	s_setprio 0
	s_barrier
	s_add_u32 s40, s40, 0x100
	s_addc_u32 s41, s41, 0
	v_lshl_add_u64 v[142:143], v[142:143], 0, s[74:75]
	v_lshl_add_u64 v[140:141], v[140:141], 0, s[74:75]
	s_cmp_ge_u32 vcc_lo, s51
	s_mov_b32 s42, vcc_lo
